# cand31 with the guard's eight-word load hoisted to the barrier entry (under the store drain) instead of beside the arrival atomic
# speedup vs baseline: 1.0037x; 1.0005x over previous
; #define GRID_BAR(seam) do { if (MK_PER_PHASE) { if (F.tid == 0) __hip_atomic_store(F.ctl + CW_TMO, 0xBADBA0u | (unsigned)(seam), RLX_AGENT); } else { XcdBarrier b_ = bar; unsigned* p_ = b_.bar; asm volatile("" : "+s"(p_)); b_.bar = p_; xcd_barrier(b_); } } while (0)
; #define BOTH(k) (IN(k) && IN((k) + 1))
; __device__ __forceinline__ void xcd_barrier(const XcdBarrier& b) {
;     asm volatile("s_waitcnt vmcnt(0)" ::: "memory");
;     __syncthreads();
;     if (threadIdx.x == 0) {
;         unsigned* bar = b.bar;
;         __builtin_amdgcn_s_waitcnt(0);
;         unsigned nloc = b.st[0], nx = b.st[1];
;         if (nloc == 0u) { xcd_barrier_complete(bar, b.x, nloc, nx); b.st[0] = nloc; b.st[1] = nx; }
; __global__ void __launch_bounds__(NWAVES * 64, 2) skel_fwd(Args args) {
;     ...
;             if (BOTH(p0 + 4)) GRID_BAR(p0 + 4);
.LBB0_575:
	v_readlane_b32 s0, v241, 48
	s_mul_i32 s0, s0, 7
	s_add_i32 s33, s0, 8
	s_cmp_ge_i32 s33, s83
	s_cbranch_scc1 .LBB0_588
	s_mov_b64 s[2:3], s[84:85]
	v_mov_b32_e32 v245, 0xc000
	global_load_dwordx4 v[246:249], v245, s[84:85] sc1
	global_load_dwordx4 v[250:253], v245, s[84:85] offset:16 sc1
	s_waitcnt vmcnt(0)
	s_waitcnt lgkmcnt(0)
	s_barrier
	s_and_saveexec_b64 s[0:1], s[86:87]
	s_cbranch_execz .LBB0_621
	v_readlane_b32 s4, v242, 49
	s_waitcnt vmcnt(0) expcnt(0) lgkmcnt(0)
	s_nop 0
	v_mov_b32_e32 v1, s4
	ds_read_b32 v4, v1
	v_readlane_b32 s4, v242, 50
	s_waitcnt lgkmcnt(0)
	v_cmp_ne_u32_e32 vcc, 0, v4
	v_mov_b32_e32 v1, s4
	ds_read_b32 v2, v1
	s_cbranch_vccnz .LBB0_592
	v_readlane_b32 s4, v243, 0
	v_readlane_b32 s5, v243, 1
	s_load_dwordx2 s[8:9], s[4:5], 0x4
	s_add_u32 s4, s2, 0x1000
	s_addc_u32 s5, s3, 0
	s_add_u32 s6, s2, 0x1100
	s_addc_u32 s7, s3, 0
	s_waitcnt lgkmcnt(0)
	s_mul_i32 s34, s8, s76
	s_add_u32 s8, s2, 0x1200
	s_mul_i32 s34, s34, s9
	s_addc_u32 s9, s3, 0
	s_add_u32 s10, s2, 0x1300
	s_addc_u32 s11, s3, 0
	s_mov_b32 s35, 1
	s_mov_b64 s[12:13], 0
	s_branch .LBB0_581

; #define GRID_BAR(seam) do { if (MK_PER_PHASE) { if (F.tid == 0) __hip_atomic_store(F.ctl + CW_TMO, 0xBADBA0u | (unsigned)(seam), RLX_AGENT); } else { XcdBarrier b_ = bar; unsigned* p_ = b_.bar; asm volatile("" : "+s"(p_)); b_.bar = p_; xcd_barrier(b_); } } while (0)
; #define BOTH(k) (IN(k) && IN((k) + 1))
; __device__ __forceinline__ void xcd_barrier(const XcdBarrier& b) {
;     asm volatile("s_waitcnt vmcnt(0)" ::: "memory");
;     __syncthreads();
;     if (threadIdx.x == 0) {
;         unsigned* bar = b.bar;
;         __builtin_amdgcn_s_waitcnt(0);
;         unsigned nloc = b.st[0], nx = b.st[1];
;         if (nloc == 0u) { xcd_barrier_complete(bar, b.x, nloc, nx); b.st[0] = nloc; b.st[1] = nx; }
; __global__ void __launch_bounds__(NWAVES * 64, 2) skel_fwd(Args args) {
;     ...
;             if (BOTH(p0 + 5)) GRID_BAR(p0 + 5);
.LBB0_641:
	v_readlane_b32 s0, v241, 48
	s_mul_i32 s0, s0, 7
	s_add_i32 s33, s0, 9
	s_cmp_ge_i32 s33, s83
	s_cbranch_scc1 .LBB0_687
	s_mov_b64 s[2:3], s[84:85]
	v_mov_b32_e32 v245, 0xc000
	global_load_dwordx4 v[246:249], v245, s[84:85] sc1
	global_load_dwordx4 v[250:253], v245, s[84:85] offset:16 sc1
	s_waitcnt vmcnt(0)
	s_waitcnt lgkmcnt(0)
	s_barrier
	s_and_saveexec_b64 s[0:1], s[86:87]
	s_cbranch_execz .LBB0_686
	v_readlane_b32 s4, v242, 49
	s_waitcnt vmcnt(0) expcnt(0) lgkmcnt(0)
	s_nop 0
	v_mov_b32_e32 v1, s4
	ds_read_b32 v4, v1
	v_readlane_b32 s4, v242, 50
	s_waitcnt lgkmcnt(0)
	v_cmp_ne_u32_e32 vcc, 0, v4
	v_mov_b32_e32 v1, s4
	ds_read_b32 v2, v1
	s_cbranch_vccnz .LBB0_657
	v_readlane_b32 s4, v243, 0
	v_readlane_b32 s5, v243, 1
	s_load_dwordx2 s[8:9], s[4:5], 0x4
	s_add_u32 s4, s2, 0x1000
	s_addc_u32 s5, s3, 0
	s_add_u32 s6, s2, 0x1100
	s_addc_u32 s7, s3, 0
	s_waitcnt lgkmcnt(0)
	s_mul_i32 s34, s8, s76
	s_add_u32 s8, s2, 0x1200
	s_mul_i32 s34, s34, s9
	s_addc_u32 s9, s3, 0
	s_add_u32 s10, s2, 0x1300
	s_addc_u32 s11, s3, 0
	s_mov_b32 s35, 1
	s_mov_b64 s[12:13], 0
	s_branch .LBB0_647

; #define GRID_BAR(seam) do { if (MK_PER_PHASE) { if (F.tid == 0) __hip_atomic_store(F.ctl + CW_TMO, 0xBADBA0u | (unsigned)(seam), RLX_AGENT); } else { XcdBarrier b_ = bar; unsigned* p_ = b_.bar; asm volatile("" : "+s"(p_)); b_.bar = p_; xcd_barrier(b_); } } while (0)
; #define BOTH(k) (IN(k) && IN((k) + 1))
; __device__ __forceinline__ void xcd_barrier(const XcdBarrier& b) {
;     asm volatile("s_waitcnt vmcnt(0)" ::: "memory");
;     __syncthreads();
;     if (threadIdx.x == 0) {
;         unsigned* bar = b.bar;
;         __builtin_amdgcn_s_waitcnt(0);
;         unsigned nloc = b.st[0], nx = b.st[1];
;         if (nloc == 0u) { xcd_barrier_complete(bar, b.x, nloc, nx); b.st[0] = nloc; b.st[1] = nx; }
; __global__ void __launch_bounds__(NWAVES * 64, 2) skel_fwd(Args args) {
;     ...
;             if (BOTH(p0 + 6)) GRID_BAR(p0 + 6);
.LBB0_763:
	v_readlane_b32 s0, v241, 43
	s_add_i32 s0, s0, 10
	s_cmp_ge_i32 s0, s83
	s_cbranch_scc1 .LBB0_776
	s_mov_b64 s[2:3], s[84:85]
	v_mov_b32_e32 v245, 0xc000
	global_load_dwordx4 v[246:249], v245, s[84:85] sc1
	global_load_dwordx4 v[250:253], v245, s[84:85] offset:16 sc1
	s_waitcnt vmcnt(0)
	s_waitcnt lgkmcnt(0)
	s_barrier
	s_and_saveexec_b64 s[0:1], s[86:87]
	s_cbranch_execz .LBB0_218
	v_readlane_b32 s4, v242, 49
	s_waitcnt vmcnt(0) expcnt(0) lgkmcnt(0)
	s_nop 0
	v_mov_b32_e32 v1, s4
	ds_read_b32 v4, v1
	v_readlane_b32 s4, v242, 50
	s_waitcnt lgkmcnt(0)
	v_cmp_ne_u32_e32 vcc, 0, v4
	v_mov_b32_e32 v1, s4
	ds_read_b32 v2, v1
	s_cbranch_vccnz .LBB0_780
	v_readlane_b32 s4, v243, 0
	v_readlane_b32 s5, v243, 1
	s_load_dwordx2 s[8:9], s[4:5], 0x4
	s_add_u32 s4, s2, 0x1000
	s_addc_u32 s5, s3, 0
	s_add_u32 s6, s2, 0x1100
	s_addc_u32 s7, s3, 0
	s_waitcnt lgkmcnt(0)
	s_mul_i32 s30, s8, s76
	s_add_u32 s8, s2, 0x1200
	s_mul_i32 s30, s30, s9
	s_addc_u32 s9, s3, 0
	s_add_u32 s10, s2, 0x1300
	s_addc_u32 s11, s3, 0
	s_mov_b32 s31, 1
	s_mov_b64 s[12:13], 0
	s_branch .LBB0_769
